# init GEMV inner loop unrolled x4 (32 weight loads in flight per wave)
# baseline (speedup 1.0000x reference)
; #define LAS __attribute__((address_space(3)))
; __device__ __forceinline__ void phase_init(const Frame& F, ArgsRef A) {
;     ...
;         const float* wp = ada_w + ((size_t)l * 2048 + F.wave * 256) * 18432 + col;
;         const LAS float* sp = sc + F.wave * 256;
; #pragma unroll 8
;         for (int k = 0; k < 256; ++k) { const f32x2 w = *(const f32x2*)(wp + (size_t)k * 18432);
; #pragma unroll
;             for (int bs = 0; bs < 9; ++bs) { const float s = sp[bs * 2048 + k]; a0[bs] += s * w.x; a1[bs] += s * w.y; } }
.LBB0_16:
	v_add_co_u32_e64 v26, s[2:3], s19, v6
	global_load_dwordx2 v[100:101], v[6:7], off
	s_nop 0
	v_addc_co_u32_e64 v27, s[2:3], -1, v7, s[2:3]
	v_add_co_u32_e64 v28, s[2:3], s20, v6
	s_add_i32 s9, s12, s8
	s_nop 0
	v_addc_co_u32_e64 v29, s[2:3], -1, v7, s[2:3]
	v_add_co_u32_e64 v30, s[2:3], s21, v6
	v_mov_b32_e32 v88, s9
	s_nop 0
	v_addc_co_u32_e64 v31, s[2:3], -1, v7, s[2:3]
	v_add_co_u32_e64 v32, s[2:3], s22, v6
	s_add_i32 s8, s8, 32
	s_nop 0
	v_addc_co_u32_e64 v33, s[2:3], -1, v7, s[2:3]
	v_add_co_u32_e64 v36, s[2:3], s13, v6
	global_load_dwordx2 v[102:103], v[26:27], off
	global_load_dwordx2 v[104:105], v[28:29], off
	global_load_dwordx2 v[106:107], v[30:31], off
	global_load_dwordx2 v[108:109], v[32:33], off
	v_addc_co_u32_e64 v37, s[2:3], 0, v7, s[2:3]
	v_add_co_u32_e64 v38, s[2:3], s23, v6
	s_nop 1
	v_addc_co_u32_e64 v39, s[2:3], 0, v7, s[2:3]
	v_add_co_u32_e64 v40, s[2:3], s24, v6
	s_nop 1
	v_addc_co_u32_e64 v41, s[2:3], 0, v7, s[2:3]
	global_load_dwordx2 v[110:111], v[36:37], off
	global_load_dwordx2 v[112:113], v[38:39], off
	global_load_dwordx2 v[114:115], v[40:41], off
	s_add_i32 s2, s9, 0x10000
	s_add_i32 s3, s9, 0x10010
	v_mov_b32_e32 v92, s2
	v_mov_b32_e32 v96, s3
	v_lshl_add_u64 v[168:169], v[6:7], 0, s[4:5]
	v_add_co_u32_e64 v170, s[2:3], s19, v168
	global_load_dwordx2 v[152:153], v[168:169], off
	s_nop 0
	v_addc_co_u32_e64 v171, s[2:3], -1, v169, s[2:3]
	v_add_co_u32_e64 v172, s[2:3], s20, v168
	s_nop 0
	s_nop 0
	v_addc_co_u32_e64 v173, s[2:3], -1, v169, s[2:3]
	v_add_co_u32_e64 v174, s[2:3], s21, v168
	s_nop 0
	s_nop 0
	v_addc_co_u32_e64 v175, s[2:3], -1, v169, s[2:3]
	v_add_co_u32_e64 v176, s[2:3], s22, v168
	s_nop 0
	s_nop 0
	v_addc_co_u32_e64 v177, s[2:3], -1, v169, s[2:3]
	v_add_co_u32_e64 v178, s[2:3], s13, v168
	global_load_dwordx2 v[154:155], v[170:171], off
	global_load_dwordx2 v[156:157], v[172:173], off
	global_load_dwordx2 v[158:159], v[174:175], off
	global_load_dwordx2 v[160:161], v[176:177], off
	v_addc_co_u32_e64 v179, s[2:3], 0, v169, s[2:3]
	v_add_co_u32_e64 v180, s[2:3], s23, v168
	s_nop 1
	v_addc_co_u32_e64 v181, s[2:3], 0, v169, s[2:3]
	v_add_co_u32_e64 v182, s[2:3], s24, v168
	s_nop 1
	v_addc_co_u32_e64 v183, s[2:3], 0, v169, s[2:3]
	global_load_dwordx2 v[162:163], v[178:179], off
	global_load_dwordx2 v[164:165], v[180:181], off
	global_load_dwordx2 v[166:167], v[182:183], off
	s_nop 0
	s_nop 0
	s_nop 0
	s_nop 0
	v_lshl_add_u64 v[168:169], v[168:169], 0, s[4:5]
	v_add_co_u32_e64 v170, s[2:3], s19, v168
	global_load_dwordx2 v[184:185], v[168:169], off
	s_nop 0
	v_addc_co_u32_e64 v171, s[2:3], -1, v169, s[2:3]
	v_add_co_u32_e64 v172, s[2:3], s20, v168
	s_nop 0
	s_nop 0
	v_addc_co_u32_e64 v173, s[2:3], -1, v169, s[2:3]
	v_add_co_u32_e64 v174, s[2:3], s21, v168
	s_nop 0
	s_nop 0
	v_addc_co_u32_e64 v175, s[2:3], -1, v169, s[2:3]
	v_add_co_u32_e64 v176, s[2:3], s22, v168
	s_nop 0
	s_nop 0
	v_addc_co_u32_e64 v177, s[2:3], -1, v169, s[2:3]
	v_add_co_u32_e64 v178, s[2:3], s13, v168
	global_load_dwordx2 v[186:187], v[170:171], off
	global_load_dwordx2 v[188:189], v[172:173], off
	global_load_dwordx2 v[190:191], v[174:175], off
	global_load_dwordx2 v[192:193], v[176:177], off
	v_addc_co_u32_e64 v179, s[2:3], 0, v169, s[2:3]
	v_add_co_u32_e64 v180, s[2:3], s23, v168
	s_nop 1
	v_addc_co_u32_e64 v181, s[2:3], 0, v169, s[2:3]
	v_add_co_u32_e64 v182, s[2:3], s24, v168
	s_nop 1
	v_addc_co_u32_e64 v183, s[2:3], 0, v169, s[2:3]
	global_load_dwordx2 v[194:195], v[178:179], off
	global_load_dwordx2 v[196:197], v[180:181], off
	global_load_dwordx2 v[198:199], v[182:183], off
	s_nop 0
	s_nop 0
	s_nop 0
	s_nop 0
	v_lshl_add_u64 v[168:169], v[168:169], 0, s[4:5]
	v_add_co_u32_e64 v170, s[2:3], s19, v168
	global_load_dwordx2 v[200:201], v[168:169], off
	s_nop 0
	v_addc_co_u32_e64 v171, s[2:3], -1, v169, s[2:3]
	v_add_co_u32_e64 v172, s[2:3], s20, v168
	s_nop 0
	s_nop 0
	v_addc_co_u32_e64 v173, s[2:3], -1, v169, s[2:3]
	v_add_co_u32_e64 v174, s[2:3], s21, v168
	s_nop 0
	s_nop 0
	v_addc_co_u32_e64 v175, s[2:3], -1, v169, s[2:3]
	v_add_co_u32_e64 v176, s[2:3], s22, v168
	s_nop 0
	s_nop 0
	v_addc_co_u32_e64 v177, s[2:3], -1, v169, s[2:3]
	v_add_co_u32_e64 v178, s[2:3], s13, v168
	global_load_dwordx2 v[202:203], v[170:171], off
	global_load_dwordx2 v[204:205], v[172:173], off
	global_load_dwordx2 v[206:207], v[174:175], off
	global_load_dwordx2 v[208:209], v[176:177], off
	v_addc_co_u32_e64 v179, s[2:3], 0, v169, s[2:3]
	v_add_co_u32_e64 v180, s[2:3], s23, v168
	s_nop 1
	v_addc_co_u32_e64 v181, s[2:3], 0, v169, s[2:3]
	v_add_co_u32_e64 v182, s[2:3], s24, v168
	s_nop 1
	v_addc_co_u32_e64 v183, s[2:3], 0, v169, s[2:3]
	global_load_dwordx2 v[210:211], v[178:179], off
	global_load_dwordx2 v[212:213], v[180:181], off
	global_load_dwordx2 v[214:215], v[182:183], off
	s_nop 0
	s_nop 0
	s_nop 0
	s_nop 0
	ds_read_b128 v[26:29], v88
	ds_read_b128 v[30:33], v88 offset:16
	ds_read_b128 v[36:39], v88 offset:8192
	ds_read_b128 v[40:43], v88 offset:8208
	ds_read_b128 v[44:47], v88 offset:16384
	ds_read_b128 v[48:51], v88 offset:16400
	ds_read_b128 v[52:55], v88 offset:24576
	ds_read_b128 v[56:59], v88 offset:24592
	ds_read_b128 v[60:63], v88 offset:32768
	ds_read_b128 v[64:67], v88 offset:32784
	ds_read_b128 v[68:71], v88 offset:40960
	ds_read_b128 v[72:75], v88 offset:40976
	ds_read_b128 v[76:79], v88 offset:49152
	ds_read_b128 v[80:83], v88 offset:49168
	ds_read_b128 v[84:87], v88 offset:57344
	ds_read_b128 v[88:91], v88 offset:57360
	ds_read_b128 v[92:95], v92
	ds_read_b128 v[96:99], v96
	s_waitcnt lgkmcnt(14)
	v_mov_b32_e32 v116, v29
	v_mov_b32_e32 v118, v39
	s_waitcnt lgkmcnt(13)
	v_mov_b32_e32 v120, v47
	s_waitcnt lgkmcnt(11)
; __device__ __forceinline__ void phase_init(const Frame& F, ArgsRef A) {
;     ...
;         for (int k = 0; k < 256; ++k) { const f32x2 w = *(const f32x2*)(wp + (size_t)k * 18432);
; #pragma unroll
;             for (int bs = 0; bs < 9; ++bs) { const float s = sp[bs * 2048 + k]; a0[bs] += s * w.x; a1[bs] += s * w.y; } }
	v_mov_b32_e32 v122, v55
	s_waitcnt lgkmcnt(9)
	v_mov_b32_e32 v124, v63
	s_waitcnt lgkmcnt(7)
	v_mov_b32_e32 v126, v71
	s_waitcnt lgkmcnt(5)
	v_mov_b32_e32 v128, v79
	s_waitcnt lgkmcnt(3)
	v_mov_b32_e32 v130, v87
	s_waitcnt lgkmcnt(1)
	v_mov_b32_e32 v148, v95
	v_mov_b32_e32 v132, v33
	v_mov_b32_e32 v134, v43
	v_mov_b32_e32 v136, v51
	v_mov_b32_e32 v138, v59
	v_mov_b32_e32 v140, v67
	v_mov_b32_e32 v142, v75
	v_mov_b32_e32 v144, v83
	v_mov_b32_e32 v146, v91
	s_waitcnt lgkmcnt(0)
	v_mov_b32_e32 v150, v99
	v_lshl_add_u64 v[6:7], v[6:7], 0, s[4:5]
	s_waitcnt vmcnt(30)
	v_pk_fma_f32 v[8:9], v[102:103], v[26:27], v[8:9] op_sel_hi:[1,0,1]
	v_pk_fma_f32 v[12:13], v[102:103], v[36:37], v[12:13] op_sel_hi:[1,0,1]
	v_pk_fma_f32 v[10:11], v[102:103], v[44:45], v[10:11] op_sel_hi:[1,0,1]
	v_pk_fma_f32 v[16:17], v[102:103], v[52:53], v[16:17] op_sel_hi:[1,0,1]
	v_pk_fma_f32 v[14:15], v[102:103], v[60:61], v[14:15] op_sel_hi:[1,0,1]
	v_pk_fma_f32 v[20:21], v[102:103], v[68:69], v[20:21] op_sel_hi:[1,0,1]
	v_pk_fma_f32 v[18:19], v[102:103], v[76:77], v[18:19] op_sel_hi:[1,0,1]
	v_pk_fma_f32 v[24:25], v[102:103], v[84:85], v[24:25] op_sel_hi:[1,0,1]
	v_pk_fma_f32 v[22:23], v[102:103], v[92:93], v[22:23] op_sel_hi:[1,0,1]
	s_waitcnt vmcnt(29)
	v_pk_fma_f32 v[8:9], v[104:105], v[26:27], v[8:9] op_sel:[0,1,0]
	v_pk_fma_f32 v[12:13], v[104:105], v[36:37], v[12:13] op_sel:[0,1,0]
	v_pk_fma_f32 v[10:11], v[104:105], v[44:45], v[10:11] op_sel:[0,1,0]
	v_pk_fma_f32 v[16:17], v[104:105], v[52:53], v[16:17] op_sel:[0,1,0]
	v_pk_fma_f32 v[14:15], v[104:105], v[60:61], v[14:15] op_sel:[0,1,0]
	v_pk_fma_f32 v[20:21], v[104:105], v[68:69], v[20:21] op_sel:[0,1,0]
	v_pk_fma_f32 v[18:19], v[104:105], v[76:77], v[18:19] op_sel:[0,1,0]
	v_pk_fma_f32 v[24:25], v[104:105], v[84:85], v[24:25] op_sel:[0,1,0]
	v_pk_fma_f32 v[22:23], v[104:105], v[92:93], v[22:23] op_sel:[0,1,0]
	s_waitcnt vmcnt(28)
	v_pk_fma_f32 v[8:9], v[106:107], v[28:29], v[8:9] op_sel_hi:[1,0,1]
	v_pk_fma_f32 v[12:13], v[106:107], v[38:39], v[12:13] op_sel_hi:[1,0,1]
	v_pk_fma_f32 v[10:11], v[106:107], v[46:47], v[10:11] op_sel_hi:[1,0,1]
	v_pk_fma_f32 v[16:17], v[106:107], v[54:55], v[16:17] op_sel_hi:[1,0,1]
	v_pk_fma_f32 v[14:15], v[106:107], v[62:63], v[14:15] op_sel_hi:[1,0,1]
	v_pk_fma_f32 v[20:21], v[106:107], v[70:71], v[20:21] op_sel_hi:[1,0,1]
	v_pk_fma_f32 v[18:19], v[106:107], v[78:79], v[18:19] op_sel_hi:[1,0,1]
	v_pk_fma_f32 v[24:25], v[106:107], v[86:87], v[24:25] op_sel_hi:[1,0,1]
	v_pk_fma_f32 v[22:23], v[106:107], v[94:95], v[22:23] op_sel_hi:[1,0,1]
	s_waitcnt vmcnt(27)
	v_pk_fma_f32 v[8:9], v[108:109], v[116:117], v[8:9] op_sel_hi:[1,0,1]
	v_pk_fma_f32 v[12:13], v[108:109], v[118:119], v[12:13] op_sel_hi:[1,0,1]
	v_pk_fma_f32 v[10:11], v[108:109], v[120:121], v[10:11] op_sel_hi:[1,0,1]
	v_pk_fma_f32 v[16:17], v[108:109], v[122:123], v[16:17] op_sel_hi:[1,0,1]
	v_pk_fma_f32 v[14:15], v[108:109], v[124:125], v[14:15] op_sel_hi:[1,0,1]
	v_pk_fma_f32 v[20:21], v[108:109], v[126:127], v[20:21] op_sel_hi:[1,0,1]
	v_pk_fma_f32 v[18:19], v[108:109], v[128:129], v[18:19] op_sel_hi:[1,0,1]
	v_pk_fma_f32 v[24:25], v[108:109], v[130:131], v[24:25] op_sel_hi:[1,0,1]
	v_pk_fma_f32 v[22:23], v[108:109], v[148:149], v[22:23] op_sel_hi:[1,0,1]
	v_pk_fma_f32 v[8:9], v[100:101], v[30:31], v[8:9] op_sel_hi:[1,0,1]
	v_pk_fma_f32 v[12:13], v[100:101], v[40:41], v[12:13] op_sel_hi:[1,0,1]
	v_pk_fma_f32 v[10:11], v[100:101], v[48:49], v[10:11] op_sel_hi:[1,0,1]
	v_pk_fma_f32 v[16:17], v[100:101], v[56:57], v[16:17] op_sel_hi:[1,0,1]
	v_pk_fma_f32 v[14:15], v[100:101], v[64:65], v[14:15] op_sel_hi:[1,0,1]
	v_pk_fma_f32 v[20:21], v[100:101], v[72:73], v[20:21] op_sel_hi:[1,0,1]
	v_pk_fma_f32 v[18:19], v[100:101], v[80:81], v[18:19] op_sel_hi:[1,0,1]
	v_pk_fma_f32 v[24:25], v[100:101], v[88:89], v[24:25] op_sel_hi:[1,0,1]
	v_pk_fma_f32 v[22:23], v[100:101], v[96:97], v[22:23] op_sel_hi:[1,0,1]
	s_waitcnt vmcnt(26)
	v_pk_fma_f32 v[8:9], v[110:111], v[30:31], v[8:9] op_sel:[0,1,0]
	v_pk_fma_f32 v[12:13], v[110:111], v[40:41], v[12:13] op_sel:[0,1,0]
	v_pk_fma_f32 v[10:11], v[110:111], v[48:49], v[10:11] op_sel:[0,1,0]
	v_pk_fma_f32 v[16:17], v[110:111], v[56:57], v[16:17] op_sel:[0,1,0]
	v_pk_fma_f32 v[14:15], v[110:111], v[64:65], v[14:15] op_sel:[0,1,0]
	v_pk_fma_f32 v[20:21], v[110:111], v[72:73], v[20:21] op_sel:[0,1,0]
	v_pk_fma_f32 v[18:19], v[110:111], v[80:81], v[18:19] op_sel:[0,1,0]
	v_pk_fma_f32 v[24:25], v[110:111], v[88:89], v[24:25] op_sel:[0,1,0]
	v_pk_fma_f32 v[22:23], v[110:111], v[96:97], v[22:23] op_sel:[0,1,0]
	s_waitcnt vmcnt(25)
	v_pk_fma_f32 v[8:9], v[112:113], v[32:33], v[8:9] op_sel_hi:[1,0,1]
	v_pk_fma_f32 v[12:13], v[112:113], v[42:43], v[12:13] op_sel_hi:[1,0,1]
	v_pk_fma_f32 v[10:11], v[112:113], v[50:51], v[10:11] op_sel_hi:[1,0,1]
	v_pk_fma_f32 v[16:17], v[112:113], v[58:59], v[16:17] op_sel_hi:[1,0,1]
	v_pk_fma_f32 v[14:15], v[112:113], v[66:67], v[14:15] op_sel_hi:[1,0,1]
	v_pk_fma_f32 v[20:21], v[112:113], v[74:75], v[20:21] op_sel_hi:[1,0,1]
	v_pk_fma_f32 v[18:19], v[112:113], v[82:83], v[18:19] op_sel_hi:[1,0,1]
	v_pk_fma_f32 v[24:25], v[112:113], v[90:91], v[24:25] op_sel_hi:[1,0,1]
	v_pk_fma_f32 v[22:23], v[112:113], v[98:99], v[22:23] op_sel_hi:[1,0,1]
	s_waitcnt vmcnt(24)
; __device__ __forceinline__ void phase_init(const Frame& F, ArgsRef A) {
;     ...
;         for (int k = 0; k < 256; ++k) { const f32x2 w = *(const f32x2*)(wp + (size_t)k * 18432);
; #pragma unroll
;             for (int bs = 0; bs < 9; ++bs) { const float s = sp[bs * 2048 + k]; a0[bs] += s * w.x; a1[bs] += s * w.y; } }
	v_pk_fma_f32 v[8:9], v[114:115], v[132:133], v[8:9] op_sel_hi:[1,0,1]
	v_pk_fma_f32 v[12:13], v[114:115], v[134:135], v[12:13] op_sel_hi:[1,0,1]
	v_pk_fma_f32 v[10:11], v[114:115], v[136:137], v[10:11] op_sel_hi:[1,0,1]
	v_pk_fma_f32 v[16:17], v[114:115], v[138:139], v[16:17] op_sel_hi:[1,0,1]
	v_pk_fma_f32 v[14:15], v[114:115], v[140:141], v[14:15] op_sel_hi:[1,0,1]
	v_pk_fma_f32 v[20:21], v[114:115], v[142:143], v[20:21] op_sel_hi:[1,0,1]
	v_pk_fma_f32 v[18:19], v[114:115], v[144:145], v[18:19] op_sel_hi:[1,0,1]
	v_pk_fma_f32 v[24:25], v[114:115], v[146:147], v[24:25] op_sel_hi:[1,0,1]
	v_pk_fma_f32 v[22:23], v[114:115], v[150:151], v[22:23] op_sel_hi:[1,0,1]
	s_add_i32 s9, s12, s8
	v_mov_b32_e32 v88, s9
	s_add_i32 s8, s8, 32
	s_add_i32 s2, s9, 0x10000
	s_add_i32 s3, s9, 0x10010
	v_mov_b32_e32 v92, s2
	v_mov_b32_e32 v96, s3
	ds_read_b128 v[26:29], v88
	ds_read_b128 v[30:33], v88 offset:16
	ds_read_b128 v[36:39], v88 offset:8192
	ds_read_b128 v[40:43], v88 offset:8208
	ds_read_b128 v[44:47], v88 offset:16384
	ds_read_b128 v[48:51], v88 offset:16400
	ds_read_b128 v[52:55], v88 offset:24576
	ds_read_b128 v[56:59], v88 offset:24592
	ds_read_b128 v[60:63], v88 offset:32768
	ds_read_b128 v[64:67], v88 offset:32784
	ds_read_b128 v[68:71], v88 offset:40960
	ds_read_b128 v[72:75], v88 offset:40976
	ds_read_b128 v[76:79], v88 offset:49152
	ds_read_b128 v[80:83], v88 offset:49168
	ds_read_b128 v[84:87], v88 offset:57344
	ds_read_b128 v[88:91], v88 offset:57360
	ds_read_b128 v[92:95], v92
	ds_read_b128 v[96:99], v96
	s_waitcnt lgkmcnt(14)
	v_mov_b32_e32 v116, v29
	v_mov_b32_e32 v118, v39
	s_waitcnt lgkmcnt(13)
	v_mov_b32_e32 v120, v47
	s_waitcnt lgkmcnt(11)
	v_mov_b32_e32 v122, v55
	s_waitcnt lgkmcnt(9)
	v_mov_b32_e32 v124, v63
	s_waitcnt lgkmcnt(7)
	v_mov_b32_e32 v126, v71
	s_waitcnt lgkmcnt(5)
	v_mov_b32_e32 v128, v79
	s_waitcnt lgkmcnt(3)
	v_mov_b32_e32 v130, v87
	s_waitcnt lgkmcnt(1)
	v_mov_b32_e32 v148, v95
	v_mov_b32_e32 v132, v33
	v_mov_b32_e32 v134, v43
	v_mov_b32_e32 v136, v51
	v_mov_b32_e32 v138, v59
	v_mov_b32_e32 v140, v67
	v_mov_b32_e32 v142, v75
	v_mov_b32_e32 v144, v83
	v_mov_b32_e32 v146, v91
	s_waitcnt lgkmcnt(0)
	v_mov_b32_e32 v150, v99
	v_lshl_add_u64 v[6:7], v[6:7], 0, s[4:5]
	s_waitcnt vmcnt(22)
	v_pk_fma_f32 v[8:9], v[154:155], v[26:27], v[8:9] op_sel_hi:[1,0,1]
	v_pk_fma_f32 v[12:13], v[154:155], v[36:37], v[12:13] op_sel_hi:[1,0,1]
	v_pk_fma_f32 v[10:11], v[154:155], v[44:45], v[10:11] op_sel_hi:[1,0,1]
	v_pk_fma_f32 v[16:17], v[154:155], v[52:53], v[16:17] op_sel_hi:[1,0,1]
	v_pk_fma_f32 v[14:15], v[154:155], v[60:61], v[14:15] op_sel_hi:[1,0,1]
	v_pk_fma_f32 v[20:21], v[154:155], v[68:69], v[20:21] op_sel_hi:[1,0,1]
	v_pk_fma_f32 v[18:19], v[154:155], v[76:77], v[18:19] op_sel_hi:[1,0,1]
	v_pk_fma_f32 v[24:25], v[154:155], v[84:85], v[24:25] op_sel_hi:[1,0,1]
	v_pk_fma_f32 v[22:23], v[154:155], v[92:93], v[22:23] op_sel_hi:[1,0,1]
	s_waitcnt vmcnt(21)
	v_pk_fma_f32 v[8:9], v[156:157], v[26:27], v[8:9] op_sel:[0,1,0]
	v_pk_fma_f32 v[12:13], v[156:157], v[36:37], v[12:13] op_sel:[0,1,0]
	v_pk_fma_f32 v[10:11], v[156:157], v[44:45], v[10:11] op_sel:[0,1,0]
	v_pk_fma_f32 v[16:17], v[156:157], v[52:53], v[16:17] op_sel:[0,1,0]
	v_pk_fma_f32 v[14:15], v[156:157], v[60:61], v[14:15] op_sel:[0,1,0]
	v_pk_fma_f32 v[20:21], v[156:157], v[68:69], v[20:21] op_sel:[0,1,0]
	v_pk_fma_f32 v[18:19], v[156:157], v[76:77], v[18:19] op_sel:[0,1,0]
	v_pk_fma_f32 v[24:25], v[156:157], v[84:85], v[24:25] op_sel:[0,1,0]
	v_pk_fma_f32 v[22:23], v[156:157], v[92:93], v[22:23] op_sel:[0,1,0]
	s_waitcnt vmcnt(20)
	v_pk_fma_f32 v[8:9], v[158:159], v[28:29], v[8:9] op_sel_hi:[1,0,1]
	v_pk_fma_f32 v[12:13], v[158:159], v[38:39], v[12:13] op_sel_hi:[1,0,1]
	v_pk_fma_f32 v[10:11], v[158:159], v[46:47], v[10:11] op_sel_hi:[1,0,1]
	v_pk_fma_f32 v[16:17], v[158:159], v[54:55], v[16:17] op_sel_hi:[1,0,1]
	v_pk_fma_f32 v[14:15], v[158:159], v[62:63], v[14:15] op_sel_hi:[1,0,1]
	v_pk_fma_f32 v[20:21], v[158:159], v[70:71], v[20:21] op_sel_hi:[1,0,1]
	v_pk_fma_f32 v[18:19], v[158:159], v[78:79], v[18:19] op_sel_hi:[1,0,1]
	v_pk_fma_f32 v[24:25], v[158:159], v[86:87], v[24:25] op_sel_hi:[1,0,1]
	v_pk_fma_f32 v[22:23], v[158:159], v[94:95], v[22:23] op_sel_hi:[1,0,1]
	s_waitcnt vmcnt(19)
	v_pk_fma_f32 v[8:9], v[160:161], v[116:117], v[8:9] op_sel_hi:[1,0,1]
	v_pk_fma_f32 v[12:13], v[160:161], v[118:119], v[12:13] op_sel_hi:[1,0,1]
	v_pk_fma_f32 v[10:11], v[160:161], v[120:121], v[10:11] op_sel_hi:[1,0,1]
	v_pk_fma_f32 v[16:17], v[160:161], v[122:123], v[16:17] op_sel_hi:[1,0,1]
	v_pk_fma_f32 v[14:15], v[160:161], v[124:125], v[14:15] op_sel_hi:[1,0,1]
	v_pk_fma_f32 v[20:21], v[160:161], v[126:127], v[20:21] op_sel_hi:[1,0,1]
	v_pk_fma_f32 v[18:19], v[160:161], v[128:129], v[18:19] op_sel_hi:[1,0,1]
	v_pk_fma_f32 v[24:25], v[160:161], v[130:131], v[24:25] op_sel_hi:[1,0,1]
	v_pk_fma_f32 v[22:23], v[160:161], v[148:149], v[22:23] op_sel_hi:[1,0,1]
	v_pk_fma_f32 v[8:9], v[152:153], v[30:31], v[8:9] op_sel_hi:[1,0,1]
	v_pk_fma_f32 v[12:13], v[152:153], v[40:41], v[12:13] op_sel_hi:[1,0,1]
	v_pk_fma_f32 v[10:11], v[152:153], v[48:49], v[10:11] op_sel_hi:[1,0,1]
	v_pk_fma_f32 v[16:17], v[152:153], v[56:57], v[16:17] op_sel_hi:[1,0,1]
	v_pk_fma_f32 v[14:15], v[152:153], v[64:65], v[14:15] op_sel_hi:[1,0,1]
	v_pk_fma_f32 v[20:21], v[152:153], v[72:73], v[20:21] op_sel_hi:[1,0,1]
	v_pk_fma_f32 v[18:19], v[152:153], v[80:81], v[18:19] op_sel_hi:[1,0,1]
	v_pk_fma_f32 v[24:25], v[152:153], v[88:89], v[24:25] op_sel_hi:[1,0,1]
	v_pk_fma_f32 v[22:23], v[152:153], v[96:97], v[22:23] op_sel_hi:[1,0,1]
	s_waitcnt vmcnt(18)
; __device__ __forceinline__ void phase_init(const Frame& F, ArgsRef A) {
;     ...
;         for (int k = 0; k < 256; ++k) { const f32x2 w = *(const f32x2*)(wp + (size_t)k * 18432);
; #pragma unroll
;             for (int bs = 0; bs < 9; ++bs) { const float s = sp[bs * 2048 + k]; a0[bs] += s * w.x; a1[bs] += s * w.y; } }
	v_pk_fma_f32 v[8:9], v[162:163], v[30:31], v[8:9] op_sel:[0,1,0]
	v_pk_fma_f32 v[12:13], v[162:163], v[40:41], v[12:13] op_sel:[0,1,0]
	v_pk_fma_f32 v[10:11], v[162:163], v[48:49], v[10:11] op_sel:[0,1,0]
	v_pk_fma_f32 v[16:17], v[162:163], v[56:57], v[16:17] op_sel:[0,1,0]
	v_pk_fma_f32 v[14:15], v[162:163], v[64:65], v[14:15] op_sel:[0,1,0]
	v_pk_fma_f32 v[20:21], v[162:163], v[72:73], v[20:21] op_sel:[0,1,0]
	v_pk_fma_f32 v[18:19], v[162:163], v[80:81], v[18:19] op_sel:[0,1,0]
	v_pk_fma_f32 v[24:25], v[162:163], v[88:89], v[24:25] op_sel:[0,1,0]
	v_pk_fma_f32 v[22:23], v[162:163], v[96:97], v[22:23] op_sel:[0,1,0]
	s_waitcnt vmcnt(17)
	v_pk_fma_f32 v[8:9], v[164:165], v[32:33], v[8:9] op_sel_hi:[1,0,1]
	v_pk_fma_f32 v[12:13], v[164:165], v[42:43], v[12:13] op_sel_hi:[1,0,1]
	v_pk_fma_f32 v[10:11], v[164:165], v[50:51], v[10:11] op_sel_hi:[1,0,1]
	v_pk_fma_f32 v[16:17], v[164:165], v[58:59], v[16:17] op_sel_hi:[1,0,1]
	v_pk_fma_f32 v[14:15], v[164:165], v[66:67], v[14:15] op_sel_hi:[1,0,1]
	v_pk_fma_f32 v[20:21], v[164:165], v[74:75], v[20:21] op_sel_hi:[1,0,1]
	v_pk_fma_f32 v[18:19], v[164:165], v[82:83], v[18:19] op_sel_hi:[1,0,1]
	v_pk_fma_f32 v[24:25], v[164:165], v[90:91], v[24:25] op_sel_hi:[1,0,1]
	v_pk_fma_f32 v[22:23], v[164:165], v[98:99], v[22:23] op_sel_hi:[1,0,1]
	s_waitcnt vmcnt(16)
	v_pk_fma_f32 v[8:9], v[166:167], v[132:133], v[8:9] op_sel_hi:[1,0,1]
	v_pk_fma_f32 v[12:13], v[166:167], v[134:135], v[12:13] op_sel_hi:[1,0,1]
	v_pk_fma_f32 v[10:11], v[166:167], v[136:137], v[10:11] op_sel_hi:[1,0,1]
	v_pk_fma_f32 v[16:17], v[166:167], v[138:139], v[16:17] op_sel_hi:[1,0,1]
	v_pk_fma_f32 v[14:15], v[166:167], v[140:141], v[14:15] op_sel_hi:[1,0,1]
	v_pk_fma_f32 v[20:21], v[166:167], v[142:143], v[20:21] op_sel_hi:[1,0,1]
	v_pk_fma_f32 v[18:19], v[166:167], v[144:145], v[18:19] op_sel_hi:[1,0,1]
	v_pk_fma_f32 v[24:25], v[166:167], v[146:147], v[24:25] op_sel_hi:[1,0,1]
	v_pk_fma_f32 v[22:23], v[166:167], v[150:151], v[22:23] op_sel_hi:[1,0,1]
	s_add_i32 s9, s12, s8
	v_mov_b32_e32 v88, s9
	s_add_i32 s8, s8, 32
	s_add_i32 s2, s9, 0x10000
	s_add_i32 s3, s9, 0x10010
	v_mov_b32_e32 v92, s2
	v_mov_b32_e32 v96, s3
	ds_read_b128 v[26:29], v88
	ds_read_b128 v[30:33], v88 offset:16
	ds_read_b128 v[36:39], v88 offset:8192
	ds_read_b128 v[40:43], v88 offset:8208
	ds_read_b128 v[44:47], v88 offset:16384
	ds_read_b128 v[48:51], v88 offset:16400
	ds_read_b128 v[52:55], v88 offset:24576
	ds_read_b128 v[56:59], v88 offset:24592
	ds_read_b128 v[60:63], v88 offset:32768
	ds_read_b128 v[64:67], v88 offset:32784
	ds_read_b128 v[68:71], v88 offset:40960
	ds_read_b128 v[72:75], v88 offset:40976
	ds_read_b128 v[76:79], v88 offset:49152
	ds_read_b128 v[80:83], v88 offset:49168
	ds_read_b128 v[84:87], v88 offset:57344
	ds_read_b128 v[88:91], v88 offset:57360
	ds_read_b128 v[92:95], v92
	ds_read_b128 v[96:99], v96
	s_waitcnt lgkmcnt(14)
	v_mov_b32_e32 v116, v29
	v_mov_b32_e32 v118, v39
	s_waitcnt lgkmcnt(13)
	v_mov_b32_e32 v120, v47
	s_waitcnt lgkmcnt(11)
	v_mov_b32_e32 v122, v55
	s_waitcnt lgkmcnt(9)
	v_mov_b32_e32 v124, v63
	s_waitcnt lgkmcnt(7)
	v_mov_b32_e32 v126, v71
	s_waitcnt lgkmcnt(5)
	v_mov_b32_e32 v128, v79
	s_waitcnt lgkmcnt(3)
	v_mov_b32_e32 v130, v87
	s_waitcnt lgkmcnt(1)
	v_mov_b32_e32 v148, v95
	v_mov_b32_e32 v132, v33
	v_mov_b32_e32 v134, v43
	v_mov_b32_e32 v136, v51
	v_mov_b32_e32 v138, v59
	v_mov_b32_e32 v140, v67
	v_mov_b32_e32 v142, v75
	v_mov_b32_e32 v144, v83
	v_mov_b32_e32 v146, v91
	s_waitcnt lgkmcnt(0)
	v_mov_b32_e32 v150, v99
	v_lshl_add_u64 v[6:7], v[6:7], 0, s[4:5]
	s_waitcnt vmcnt(14)
	v_pk_fma_f32 v[8:9], v[186:187], v[26:27], v[8:9] op_sel_hi:[1,0,1]
	v_pk_fma_f32 v[12:13], v[186:187], v[36:37], v[12:13] op_sel_hi:[1,0,1]
	v_pk_fma_f32 v[10:11], v[186:187], v[44:45], v[10:11] op_sel_hi:[1,0,1]
	v_pk_fma_f32 v[16:17], v[186:187], v[52:53], v[16:17] op_sel_hi:[1,0,1]
	v_pk_fma_f32 v[14:15], v[186:187], v[60:61], v[14:15] op_sel_hi:[1,0,1]
	v_pk_fma_f32 v[20:21], v[186:187], v[68:69], v[20:21] op_sel_hi:[1,0,1]
	v_pk_fma_f32 v[18:19], v[186:187], v[76:77], v[18:19] op_sel_hi:[1,0,1]
	v_pk_fma_f32 v[24:25], v[186:187], v[84:85], v[24:25] op_sel_hi:[1,0,1]
	v_pk_fma_f32 v[22:23], v[186:187], v[92:93], v[22:23] op_sel_hi:[1,0,1]
	s_waitcnt vmcnt(13)
	v_pk_fma_f32 v[8:9], v[188:189], v[26:27], v[8:9] op_sel:[0,1,0]
	v_pk_fma_f32 v[12:13], v[188:189], v[36:37], v[12:13] op_sel:[0,1,0]
	v_pk_fma_f32 v[10:11], v[188:189], v[44:45], v[10:11] op_sel:[0,1,0]
	v_pk_fma_f32 v[16:17], v[188:189], v[52:53], v[16:17] op_sel:[0,1,0]
	v_pk_fma_f32 v[14:15], v[188:189], v[60:61], v[14:15] op_sel:[0,1,0]
	v_pk_fma_f32 v[20:21], v[188:189], v[68:69], v[20:21] op_sel:[0,1,0]
	v_pk_fma_f32 v[18:19], v[188:189], v[76:77], v[18:19] op_sel:[0,1,0]
	v_pk_fma_f32 v[24:25], v[188:189], v[84:85], v[24:25] op_sel:[0,1,0]
	v_pk_fma_f32 v[22:23], v[188:189], v[92:93], v[22:23] op_sel:[0,1,0]
	s_waitcnt vmcnt(12)
	v_pk_fma_f32 v[8:9], v[190:191], v[28:29], v[8:9] op_sel_hi:[1,0,1]
	v_pk_fma_f32 v[12:13], v[190:191], v[38:39], v[12:13] op_sel_hi:[1,0,1]
	v_pk_fma_f32 v[10:11], v[190:191], v[46:47], v[10:11] op_sel_hi:[1,0,1]
	v_pk_fma_f32 v[16:17], v[190:191], v[54:55], v[16:17] op_sel_hi:[1,0,1]
	v_pk_fma_f32 v[14:15], v[190:191], v[62:63], v[14:15] op_sel_hi:[1,0,1]
	v_pk_fma_f32 v[20:21], v[190:191], v[70:71], v[20:21] op_sel_hi:[1,0,1]
	v_pk_fma_f32 v[18:19], v[190:191], v[78:79], v[18:19] op_sel_hi:[1,0,1]
	v_pk_fma_f32 v[24:25], v[190:191], v[86:87], v[24:25] op_sel_hi:[1,0,1]
	v_pk_fma_f32 v[22:23], v[190:191], v[94:95], v[22:23] op_sel_hi:[1,0,1]
	s_waitcnt vmcnt(11)
; __device__ __forceinline__ void phase_init(const Frame& F, ArgsRef A) {
;     ...
;         for (int k = 0; k < 256; ++k) { const f32x2 w = *(const f32x2*)(wp + (size_t)k * 18432);
; #pragma unroll
;             for (int bs = 0; bs < 9; ++bs) { const float s = sp[bs * 2048 + k]; a0[bs] += s * w.x; a1[bs] += s * w.y; } }
	v_pk_fma_f32 v[8:9], v[192:193], v[116:117], v[8:9] op_sel_hi:[1,0,1]
	v_pk_fma_f32 v[12:13], v[192:193], v[118:119], v[12:13] op_sel_hi:[1,0,1]
	v_pk_fma_f32 v[10:11], v[192:193], v[120:121], v[10:11] op_sel_hi:[1,0,1]
	v_pk_fma_f32 v[16:17], v[192:193], v[122:123], v[16:17] op_sel_hi:[1,0,1]
	v_pk_fma_f32 v[14:15], v[192:193], v[124:125], v[14:15] op_sel_hi:[1,0,1]
	v_pk_fma_f32 v[20:21], v[192:193], v[126:127], v[20:21] op_sel_hi:[1,0,1]
	v_pk_fma_f32 v[18:19], v[192:193], v[128:129], v[18:19] op_sel_hi:[1,0,1]
	v_pk_fma_f32 v[24:25], v[192:193], v[130:131], v[24:25] op_sel_hi:[1,0,1]
	v_pk_fma_f32 v[22:23], v[192:193], v[148:149], v[22:23] op_sel_hi:[1,0,1]
	v_pk_fma_f32 v[8:9], v[184:185], v[30:31], v[8:9] op_sel_hi:[1,0,1]
	v_pk_fma_f32 v[12:13], v[184:185], v[40:41], v[12:13] op_sel_hi:[1,0,1]
	v_pk_fma_f32 v[10:11], v[184:185], v[48:49], v[10:11] op_sel_hi:[1,0,1]
	v_pk_fma_f32 v[16:17], v[184:185], v[56:57], v[16:17] op_sel_hi:[1,0,1]
	v_pk_fma_f32 v[14:15], v[184:185], v[64:65], v[14:15] op_sel_hi:[1,0,1]
	v_pk_fma_f32 v[20:21], v[184:185], v[72:73], v[20:21] op_sel_hi:[1,0,1]
	v_pk_fma_f32 v[18:19], v[184:185], v[80:81], v[18:19] op_sel_hi:[1,0,1]
	v_pk_fma_f32 v[24:25], v[184:185], v[88:89], v[24:25] op_sel_hi:[1,0,1]
	v_pk_fma_f32 v[22:23], v[184:185], v[96:97], v[22:23] op_sel_hi:[1,0,1]
	s_waitcnt vmcnt(10)
	v_pk_fma_f32 v[8:9], v[194:195], v[30:31], v[8:9] op_sel:[0,1,0]
	v_pk_fma_f32 v[12:13], v[194:195], v[40:41], v[12:13] op_sel:[0,1,0]
	v_pk_fma_f32 v[10:11], v[194:195], v[48:49], v[10:11] op_sel:[0,1,0]
	v_pk_fma_f32 v[16:17], v[194:195], v[56:57], v[16:17] op_sel:[0,1,0]
	v_pk_fma_f32 v[14:15], v[194:195], v[64:65], v[14:15] op_sel:[0,1,0]
	v_pk_fma_f32 v[20:21], v[194:195], v[72:73], v[20:21] op_sel:[0,1,0]
	v_pk_fma_f32 v[18:19], v[194:195], v[80:81], v[18:19] op_sel:[0,1,0]
	v_pk_fma_f32 v[24:25], v[194:195], v[88:89], v[24:25] op_sel:[0,1,0]
	v_pk_fma_f32 v[22:23], v[194:195], v[96:97], v[22:23] op_sel:[0,1,0]
	s_waitcnt vmcnt(9)
	v_pk_fma_f32 v[8:9], v[196:197], v[32:33], v[8:9] op_sel_hi:[1,0,1]
	v_pk_fma_f32 v[12:13], v[196:197], v[42:43], v[12:13] op_sel_hi:[1,0,1]
	v_pk_fma_f32 v[10:11], v[196:197], v[50:51], v[10:11] op_sel_hi:[1,0,1]
	v_pk_fma_f32 v[16:17], v[196:197], v[58:59], v[16:17] op_sel_hi:[1,0,1]
	v_pk_fma_f32 v[14:15], v[196:197], v[66:67], v[14:15] op_sel_hi:[1,0,1]
	v_pk_fma_f32 v[20:21], v[196:197], v[74:75], v[20:21] op_sel_hi:[1,0,1]
	v_pk_fma_f32 v[18:19], v[196:197], v[82:83], v[18:19] op_sel_hi:[1,0,1]
	v_pk_fma_f32 v[24:25], v[196:197], v[90:91], v[24:25] op_sel_hi:[1,0,1]
	v_pk_fma_f32 v[22:23], v[196:197], v[98:99], v[22:23] op_sel_hi:[1,0,1]
	s_waitcnt vmcnt(8)
	v_pk_fma_f32 v[8:9], v[198:199], v[132:133], v[8:9] op_sel_hi:[1,0,1]
	v_pk_fma_f32 v[12:13], v[198:199], v[134:135], v[12:13] op_sel_hi:[1,0,1]
	v_pk_fma_f32 v[10:11], v[198:199], v[136:137], v[10:11] op_sel_hi:[1,0,1]
	v_pk_fma_f32 v[16:17], v[198:199], v[138:139], v[16:17] op_sel_hi:[1,0,1]
	v_pk_fma_f32 v[14:15], v[198:199], v[140:141], v[14:15] op_sel_hi:[1,0,1]
	v_pk_fma_f32 v[20:21], v[198:199], v[142:143], v[20:21] op_sel_hi:[1,0,1]
	v_pk_fma_f32 v[18:19], v[198:199], v[144:145], v[18:19] op_sel_hi:[1,0,1]
	v_pk_fma_f32 v[24:25], v[198:199], v[146:147], v[24:25] op_sel_hi:[1,0,1]
	v_pk_fma_f32 v[22:23], v[198:199], v[150:151], v[22:23] op_sel_hi:[1,0,1]
	s_add_i32 s9, s12, s8
	v_mov_b32_e32 v88, s9
	s_add_i32 s8, s8, 32
	s_add_i32 s2, s9, 0x10000
	s_add_i32 s3, s9, 0x10010
	v_mov_b32_e32 v92, s2
	v_mov_b32_e32 v96, s3
	ds_read_b128 v[26:29], v88
	ds_read_b128 v[30:33], v88 offset:16
	ds_read_b128 v[36:39], v88 offset:8192
	ds_read_b128 v[40:43], v88 offset:8208
	ds_read_b128 v[44:47], v88 offset:16384
	ds_read_b128 v[48:51], v88 offset:16400
	ds_read_b128 v[52:55], v88 offset:24576
	ds_read_b128 v[56:59], v88 offset:24592
	ds_read_b128 v[60:63], v88 offset:32768
	ds_read_b128 v[64:67], v88 offset:32784
	ds_read_b128 v[68:71], v88 offset:40960
	ds_read_b128 v[72:75], v88 offset:40976
	ds_read_b128 v[76:79], v88 offset:49152
	ds_read_b128 v[80:83], v88 offset:49168
	ds_read_b128 v[84:87], v88 offset:57344
	ds_read_b128 v[88:91], v88 offset:57360
	ds_read_b128 v[92:95], v92
	ds_read_b128 v[96:99], v96
	s_waitcnt lgkmcnt(14)
	v_mov_b32_e32 v116, v29
	v_mov_b32_e32 v118, v39
	s_waitcnt lgkmcnt(13)
	v_mov_b32_e32 v120, v47
	s_waitcnt lgkmcnt(11)
	v_mov_b32_e32 v122, v55
	s_waitcnt lgkmcnt(9)
	v_mov_b32_e32 v124, v63
	s_waitcnt lgkmcnt(7)
	v_mov_b32_e32 v126, v71
	s_waitcnt lgkmcnt(5)
	v_mov_b32_e32 v128, v79
	s_waitcnt lgkmcnt(3)
	v_mov_b32_e32 v130, v87
	s_waitcnt lgkmcnt(1)
	v_mov_b32_e32 v148, v95
	v_mov_b32_e32 v132, v33
	v_mov_b32_e32 v134, v43
	v_mov_b32_e32 v136, v51
	v_mov_b32_e32 v138, v59
	v_mov_b32_e32 v140, v67
	v_mov_b32_e32 v142, v75
	v_mov_b32_e32 v144, v83
	v_mov_b32_e32 v146, v91
	s_waitcnt lgkmcnt(0)
	v_mov_b32_e32 v150, v99
	v_lshl_add_u64 v[6:7], v[6:7], 0, s[4:5]
	s_cmpk_eq_i32 s8, 0x400
	s_waitcnt vmcnt(6)
	v_pk_fma_f32 v[8:9], v[202:203], v[26:27], v[8:9] op_sel_hi:[1,0,1]
	v_pk_fma_f32 v[12:13], v[202:203], v[36:37], v[12:13] op_sel_hi:[1,0,1]
	v_pk_fma_f32 v[10:11], v[202:203], v[44:45], v[10:11] op_sel_hi:[1,0,1]
	v_pk_fma_f32 v[16:17], v[202:203], v[52:53], v[16:17] op_sel_hi:[1,0,1]
	v_pk_fma_f32 v[14:15], v[202:203], v[60:61], v[14:15] op_sel_hi:[1,0,1]
	v_pk_fma_f32 v[20:21], v[202:203], v[68:69], v[20:21] op_sel_hi:[1,0,1]
	v_pk_fma_f32 v[18:19], v[202:203], v[76:77], v[18:19] op_sel_hi:[1,0,1]
	v_pk_fma_f32 v[24:25], v[202:203], v[84:85], v[24:25] op_sel_hi:[1,0,1]
	v_pk_fma_f32 v[22:23], v[202:203], v[92:93], v[22:23] op_sel_hi:[1,0,1]
	s_waitcnt vmcnt(5)
; __device__ __forceinline__ void phase_init(const Frame& F, ArgsRef A) {
;     ...
;         for (int k = 0; k < 256; ++k) { const f32x2 w = *(const f32x2*)(wp + (size_t)k * 18432);
; #pragma unroll
;             for (int bs = 0; bs < 9; ++bs) { const float s = sp[bs * 2048 + k]; a0[bs] += s * w.x; a1[bs] += s * w.y; } }
; #pragma unroll
;         for (int bs = 0; bs < 9; ++bs) { red[(F.wave * 9 + bs) * 128 + 2 * F.lane] = a0[bs]; red[(F.wave * 9 + bs) * 128 + 2 * F.lane + 1] = a1[bs]; }
;         __syncthreads();
;         for (int o = F.tid; o < 9 * 128; o += NTHR) { const int bs = o >> 7, cc = o & 127; float s = ada_b[l * 18432 + cb * 128 + cc];
; #pragma unroll
;             for (int w = 0; w < 8; ++w) s += red[(w * 9 + bs) * 128 + cc];
;             mods[((size_t)l * 9 + bs) * 18432 + cb * 128 + cc] = s; }
	v_pk_fma_f32 v[8:9], v[204:205], v[26:27], v[8:9] op_sel:[0,1,0]
	v_pk_fma_f32 v[12:13], v[204:205], v[36:37], v[12:13] op_sel:[0,1,0]
	v_pk_fma_f32 v[10:11], v[204:205], v[44:45], v[10:11] op_sel:[0,1,0]
	v_pk_fma_f32 v[16:17], v[204:205], v[52:53], v[16:17] op_sel:[0,1,0]
	v_pk_fma_f32 v[14:15], v[204:205], v[60:61], v[14:15] op_sel:[0,1,0]
	v_pk_fma_f32 v[20:21], v[204:205], v[68:69], v[20:21] op_sel:[0,1,0]
	v_pk_fma_f32 v[18:19], v[204:205], v[76:77], v[18:19] op_sel:[0,1,0]
	v_pk_fma_f32 v[24:25], v[204:205], v[84:85], v[24:25] op_sel:[0,1,0]
	v_pk_fma_f32 v[22:23], v[204:205], v[92:93], v[22:23] op_sel:[0,1,0]
	s_waitcnt vmcnt(4)
	v_pk_fma_f32 v[8:9], v[206:207], v[28:29], v[8:9] op_sel_hi:[1,0,1]
	v_pk_fma_f32 v[12:13], v[206:207], v[38:39], v[12:13] op_sel_hi:[1,0,1]
	v_pk_fma_f32 v[10:11], v[206:207], v[46:47], v[10:11] op_sel_hi:[1,0,1]
	v_pk_fma_f32 v[16:17], v[206:207], v[54:55], v[16:17] op_sel_hi:[1,0,1]
	v_pk_fma_f32 v[14:15], v[206:207], v[62:63], v[14:15] op_sel_hi:[1,0,1]
	v_pk_fma_f32 v[20:21], v[206:207], v[70:71], v[20:21] op_sel_hi:[1,0,1]
	v_pk_fma_f32 v[18:19], v[206:207], v[78:79], v[18:19] op_sel_hi:[1,0,1]
	v_pk_fma_f32 v[24:25], v[206:207], v[86:87], v[24:25] op_sel_hi:[1,0,1]
	v_pk_fma_f32 v[22:23], v[206:207], v[94:95], v[22:23] op_sel_hi:[1,0,1]
	s_waitcnt vmcnt(3)
	v_pk_fma_f32 v[8:9], v[208:209], v[116:117], v[8:9] op_sel_hi:[1,0,1]
	v_pk_fma_f32 v[12:13], v[208:209], v[118:119], v[12:13] op_sel_hi:[1,0,1]
	v_pk_fma_f32 v[10:11], v[208:209], v[120:121], v[10:11] op_sel_hi:[1,0,1]
	v_pk_fma_f32 v[16:17], v[208:209], v[122:123], v[16:17] op_sel_hi:[1,0,1]
	v_pk_fma_f32 v[14:15], v[208:209], v[124:125], v[14:15] op_sel_hi:[1,0,1]
	v_pk_fma_f32 v[20:21], v[208:209], v[126:127], v[20:21] op_sel_hi:[1,0,1]
	v_pk_fma_f32 v[18:19], v[208:209], v[128:129], v[18:19] op_sel_hi:[1,0,1]
	v_pk_fma_f32 v[24:25], v[208:209], v[130:131], v[24:25] op_sel_hi:[1,0,1]
	v_pk_fma_f32 v[22:23], v[208:209], v[148:149], v[22:23] op_sel_hi:[1,0,1]
	v_pk_fma_f32 v[8:9], v[200:201], v[30:31], v[8:9] op_sel_hi:[1,0,1]
	v_pk_fma_f32 v[12:13], v[200:201], v[40:41], v[12:13] op_sel_hi:[1,0,1]
	v_pk_fma_f32 v[10:11], v[200:201], v[48:49], v[10:11] op_sel_hi:[1,0,1]
	v_pk_fma_f32 v[16:17], v[200:201], v[56:57], v[16:17] op_sel_hi:[1,0,1]
	v_pk_fma_f32 v[14:15], v[200:201], v[64:65], v[14:15] op_sel_hi:[1,0,1]
	v_pk_fma_f32 v[20:21], v[200:201], v[72:73], v[20:21] op_sel_hi:[1,0,1]
	v_pk_fma_f32 v[18:19], v[200:201], v[80:81], v[18:19] op_sel_hi:[1,0,1]
	v_pk_fma_f32 v[24:25], v[200:201], v[88:89], v[24:25] op_sel_hi:[1,0,1]
	v_pk_fma_f32 v[22:23], v[200:201], v[96:97], v[22:23] op_sel_hi:[1,0,1]
	s_waitcnt vmcnt(2)
	v_pk_fma_f32 v[8:9], v[210:211], v[30:31], v[8:9] op_sel:[0,1,0]
	v_pk_fma_f32 v[12:13], v[210:211], v[40:41], v[12:13] op_sel:[0,1,0]
	v_pk_fma_f32 v[10:11], v[210:211], v[48:49], v[10:11] op_sel:[0,1,0]
	v_pk_fma_f32 v[16:17], v[210:211], v[56:57], v[16:17] op_sel:[0,1,0]
	v_pk_fma_f32 v[14:15], v[210:211], v[64:65], v[14:15] op_sel:[0,1,0]
	v_pk_fma_f32 v[20:21], v[210:211], v[72:73], v[20:21] op_sel:[0,1,0]
	v_pk_fma_f32 v[18:19], v[210:211], v[80:81], v[18:19] op_sel:[0,1,0]
	v_pk_fma_f32 v[24:25], v[210:211], v[88:89], v[24:25] op_sel:[0,1,0]
	v_pk_fma_f32 v[22:23], v[210:211], v[96:97], v[22:23] op_sel:[0,1,0]
	s_waitcnt vmcnt(1)
	v_pk_fma_f32 v[8:9], v[212:213], v[32:33], v[8:9] op_sel_hi:[1,0,1]
	v_pk_fma_f32 v[12:13], v[212:213], v[42:43], v[12:13] op_sel_hi:[1,0,1]
	v_pk_fma_f32 v[10:11], v[212:213], v[50:51], v[10:11] op_sel_hi:[1,0,1]
	v_pk_fma_f32 v[16:17], v[212:213], v[58:59], v[16:17] op_sel_hi:[1,0,1]
	v_pk_fma_f32 v[14:15], v[212:213], v[66:67], v[14:15] op_sel_hi:[1,0,1]
	v_pk_fma_f32 v[20:21], v[212:213], v[74:75], v[20:21] op_sel_hi:[1,0,1]
	v_pk_fma_f32 v[18:19], v[212:213], v[82:83], v[18:19] op_sel_hi:[1,0,1]
	v_pk_fma_f32 v[24:25], v[212:213], v[90:91], v[24:25] op_sel_hi:[1,0,1]
	v_pk_fma_f32 v[22:23], v[212:213], v[98:99], v[22:23] op_sel_hi:[1,0,1]
	s_waitcnt vmcnt(0)
	v_pk_fma_f32 v[8:9], v[214:215], v[132:133], v[8:9] op_sel_hi:[1,0,1]
	v_pk_fma_f32 v[12:13], v[214:215], v[134:135], v[12:13] op_sel_hi:[1,0,1]
	v_pk_fma_f32 v[10:11], v[214:215], v[136:137], v[10:11] op_sel_hi:[1,0,1]
	v_pk_fma_f32 v[16:17], v[214:215], v[138:139], v[16:17] op_sel_hi:[1,0,1]
	v_pk_fma_f32 v[14:15], v[214:215], v[140:141], v[14:15] op_sel_hi:[1,0,1]
	v_pk_fma_f32 v[20:21], v[214:215], v[142:143], v[20:21] op_sel_hi:[1,0,1]
	v_pk_fma_f32 v[18:19], v[214:215], v[144:145], v[18:19] op_sel_hi:[1,0,1]
	v_pk_fma_f32 v[24:25], v[214:215], v[146:147], v[24:25] op_sel_hi:[1,0,1]
	v_pk_fma_f32 v[22:23], v[214:215], v[150:151], v[22:23] op_sel_hi:[1,0,1]
	s_cbranch_scc0 .LBB0_16
	ds_write2st64_b64 v2, v[8:9], v[12:13] offset1:1
	ds_write2st64_b64 v2, v[10:11], v[16:17] offset0:2 offset1:3
	ds_write2st64_b64 v2, v[14:15], v[20:21] offset0:4 offset1:5
	ds_write2st64_b64 v2, v[18:19], v[24:25] offset0:6 offset1:7
	ds_write_b64 v2, v[22:23] offset:4096
	s_waitcnt lgkmcnt(0)
	s_barrier
	s_and_saveexec_b64 s[8:9], vcc
	s_cbranch_execz .LBB0_14
	s_mul_i32 s2, s7, 0x4800
	s_add_i32 s2, s2, s6
	v_or_b32_e32 v6, s2, v34
	s_mul_hi_i32 s11, s7, 9
	s_mul_i32 s10, s7, 9
	s_ashr_i32 s7, s6, 31
	v_ashrrev_i32_e32 v7, 31, v6
	v_lshl_add_u64 v[6:7], v[6:7], 2, s[0:1]
	v_lshl_add_u64 v[8:9], s[6:7], 2, v[4:5]
	s_mov_b64 s[6:7], 0
	v_mov_b32_e32 v10, v0
